# P0 transposes rebalanced: workgroups that also build the S5 matrices take 10 fewer items each
# baseline (speedup 1.0000x reference)
; __device__ __forceinline__ void transpose_item(const float* W, int K, int N, bf16_t* WT, LAS float* scr, int item, int lane, const float* gam, const float* bet, float* sdst) {
;     const int nblk = N / 32, nbg = (nblk + 7) >> 3, g64 = item >> 6, r = item & 63;
;     const int nb = (g64 % nbg) * 8 + (r & 7), kb = (g64 / nbg) * 8 + (r >> 3), k0 = 64 * kb, n0 = 32 * nb;
;     if (nb >= nblk) return;
; #pragma unroll
;     for (int i = 0; i < 8; ++i) { const int kk = 8 * i + (lane >> 3), n4 = (lane & 7) * 4;
; __global__ void __launch_bounds__(NTHR, 2) mega_fwd(Args) {
;     ...
;             constexpr int NI0 = 64 * 256, NI1 = 32 * 64, NI2 = 64 * 128, NI3 = 64 * 512, NI4 = 256 * 128, NI5 = 64 * 8 * ((FOX_IN / 32 + 7) / 8), NI6 = 64 * 128, NI7 = NI3, NI8 = NI4;
;             constexpr int NITOT = NI0 + NI1 + NI2 + NI3 + NI4 + NI5 + NI6 + NI7 + NI8;
;             for (int it = gw; it < NITOT; it += NGW) {
;                 int r = it; const float* src; bf16_t* dst; int KK, NN; const float* gam = nullptr; const float* bet = nullptr; float* sd = nullptr;
;                 if (r < NI0) { src = INP(1); KK = 4096; NN = 8192; dst = WSP(bf16_t, WS_W_IN0); }
;                 else if ((r -= NI0) < NI1) { src = INP(10); KK = 2048; NN = 2048; dst = WSP(bf16_t, WS_W_GLU); }
;                 else if ((r -= NI1) < NI2) { src = INP(11); KK = 4096; NN = 4096; dst = WSP(bf16_t, WS_W_OUT0); }
;                 else if ((r -= NI2) < NI3) { src = INP(17); KK = 4096; NN = 16384; dst = WSP(bf16_t, WS_W1_0); gam = INP(15); bet = INP(16); sd = WSP(float, WS_ST); }
;                 else if ((r -= NI3) < NI4) { src = INP(18); KK = 16384; NN = 4096; dst = WSP(bf16_t, WS_W2_0); }
;                 else if ((r -= NI4) < NI5) { src = INP(12); KK = 4096; NN = FOX_IN; dst = WSP(bf16_t, WS_W_IN1); gam = INP(19); bet = INP(20); sd = WSP(float, WS_ST) + 2 * ST_N; }
;                 else if ((r -= NI5) < NI6) { src = INP(14); KK = 4096; NN = 4096; dst = WSP(bf16_t, WS_W_OUT1); }
;                 else if ((r -= NI6) < NI7) { src = INP(17) + (size_t)4096 * 16384; KK = 4096; NN = 16384; dst = WSP(bf16_t, WS_W1_1); gam = INP(15) + DM; bet = INP(16) + DM; sd = WSP(float, WS_ST) + 4 * ST_N; }
;                 else { r -= NI7; src = INP(18) + (size_t)4096 * 16384; KK = 16384; NN = 4096; dst = WSP(bf16_t, WS_W2_1); }
;                 transpose_item(src, KK, NN, dst, scr, r, lane, gam, bet, sd);
.LBB0_42:
	s_cmp_gt_i32 s36, 0x2e9ff
	v_readlane_b32 s92, v248, 4
	s_cbranch_scc1 .LBB0_87
	s_lshl_b32 s3, s92, 14
	s_add_i32 s8, s3, 0
	s_waitcnt lgkmcnt(0)
	s_add_u32 s6, s48, 0x26b00000
	s_addc_u32 s7, s49, 0
	s_add_u32 s12, s48, 0x1eb00000
	s_addc_u32 s13, s49, 0
	s_add_u32 s14, s48, 0x50000
	s_addc_u32 s15, s49, 0
	s_add_u32 s16, s48, 0x1cb00000
	s_addc_u32 s17, s49, 0
	s_add_u32 s20, s48, 0x16900000
	s_addc_u32 s21, s49, 0
	s_add_u32 s22, s48, 0x30000
	s_addc_u32 s23, s49, 0
	s_add_u32 s24, s48, 0xe900000
	s_addc_u32 s25, s49, 0
	s_add_u32 s26, s48, 0x6900000
	s_addc_u32 s27, s49, 0
	s_add_u32 s28, s48, 0x10000
	v_lshlrev_b32_e32 v2, 3, v4
	s_addc_u32 s29, s49, 0
	v_ashrrev_i32_e32 v8, 3, v4
	v_and_b32_e32 v2, 56, v2
	s_add_u32 s30, s48, 0x4900000
	v_and_b32_e32 v0, 28, v5
	v_mul_u32_u24_e32 v13, 0x84, v2
	v_lshlrev_b32_e32 v14, 2, v8
	v_lshrrev_b32_e32 v15, 5, v4
	s_addc_u32 s31, s49, 0
	v_lshl_add_u32 v3, v0, 2, s8
	v_add_u32_e32 v12, s8, v5
	v_add3_u32 v13, s8, v13, v14
	v_lshl_add_u32 v14, v15, 7, s8
	s_movk_i32 s8, 0x1080
	s_add_u32 s50, s48, 0x4100000
	s_movk_i32 s4, 0x84
	v_mul_lo_u32 v15, v15, s8
	s_addc_u32 s51, s49, 0
	v_mul_lo_u32 v6, v8, s4
	v_and_b32_e32 v7, 31, v4
	v_add_u32_e32 v15, s3, v15
	s_add_u32 s54, s48, 0x100000
	v_lshl_or_b32 v7, v7, 2, v15
	v_add_u32_e32 v16, v3, v6
	v_mbcnt_lo_u32_b32 v3, -1, 0
	s_addc_u32 s55, s49, 0
	v_mov_b32_e32 v1, 0
	v_add_u32_e32 v9, 8, v8
	v_add_u32_e32 v10, 16, v8
	v_add_u32_e32 v11, 24, v8
	v_cmp_gt_i32_e64 s[4:5], 32, v4
	v_ashrrev_i32_e32 v5, 31, v4
	v_add_u32_e32 v14, 0x2100, v14
	v_add_u32_e32 v15, 0, v7
	v_lshlrev_b32_e32 v0, 2, v0
	v_add_u32_e32 v17, 0x420, v16
	v_add_u32_e32 v18, 0x428, v16
	v_add_u32_e32 v19, 0x840, v16
	v_add_u32_e32 v20, 0x848, v16
	v_add_u32_e32 v21, 0xc60, v16
	v_add_u32_e32 v22, 0xc68, v16
	v_add_u32_e32 v23, 0x1080, v16
	v_add_u32_e32 v24, 0x1088, v16
	v_add_u32_e32 v25, 0x14a0, v16
	v_add_u32_e32 v26, 0x14a8, v16
	v_add_u32_e32 v27, 0x18c0, v16
	v_add_u32_e32 v28, 0x18c8, v16
	v_add_u32_e32 v29, 0x1ce0, v16
	v_add_u32_e32 v30, 0x1ce8, v16
	s_movk_i32 s3, 0x7fff
	s_mov_b32 s35, 0xffff0000
	v_lshlrev_b32_e32 v2, 1, v2
	v_mbcnt_hi_u32_b32 v31, -1, v3
	s_nop 1
	v_writelane_b32 v248, s34, 53
	s_mov_b32 s62, 0x2e9ff
	s_mov_b32 s63, -1
	s_cmpk_lg_i32 s40, 0x100
	s_cbranch_scc1 .Lrb_set
	s_mov_b32 s62, 0x2c1ff
	s_cmpk_lt_i32 s36, 0x400
	s_cbranch_scc1 .Lrb_set
	s_add_i32 s63, s36, 0x2be00
.Lrb_set:
	s_nop 1
	v_writelane_b32 v248, s62, 54
	s_nop 1
	v_writelane_b32 v248, s63, 55
	s_nop 1
	s_mov_b32 s41, s36
	s_branch .LBB0_47

; __global__ void __launch_bounds__(NTHR, 2) mega_fwd(Args) {
;     ...
;             for (int it = gw; it < NITOT; it += NGW) {
.LBB0_46:
	v_readlane_b32 s8, v248, 53
	v_readlane_b32 s9, v248, 54
	s_nop 1
	s_add_i32 s41, s41, s8
	s_cmp_gt_i32 s41, s9
	s_cbranch_scc0 .LBB0_47
	v_readlane_b32 s8, v248, 55
	s_nop 1
	s_cmp_lt_i32 s8, 0
	s_cbranch_scc1 .LBB0_87
	s_mov_b32 s41, s8
	s_movk_i32 s8, 0x400
	s_nop 1
	v_writelane_b32 v248, s8, 53
	s_mov_b32 s8, 0x2e9ff
	s_nop 1
	v_writelane_b32 v248, s8, 54
	s_mov_b32 s8, -1
	s_nop 1
	v_writelane_b32 v248, s8, 55
	s_nop 1
